# +E13 group A/B workgroups request their skinny task's weight panel (results unused) before parking in the stage wait, so the k-loop reads it from L2
# speedup vs baseline: 1.0118x; 1.0016x over previous
; __device__ __forceinline__ unsigned xb_ld(unsigned* p)              { return __hip_atomic_load(p, __ATOMIC_RELAXED, __HIP_MEMORY_SCOPE_AGENT); }
; #define XB_SPIN(cond, bar) do { unsigned _sp = 0; while (cond) { __builtin_amdgcn_s_sleep(1); \
;     if ((++_sp & 255u) == 0u) { if (xb_ld(&(bar)[XB_TMO])) break; if (_sp > XB_SPIN_CAP) { atomicAdd(&(bar)[XB_TMO], 1u); break; } } } } while (0)
; __device__ __forceinline__ void stage_wait(unsigned* ctr, unsigned want, unsigned* bar) {
;     if (threadIdx.x == 0) { XB_SPIN(xb_ld(ctr) < want, bar); __builtin_amdgcn_fence(__ATOMIC_ACQUIRE, "agent"); asm volatile("s_waitcnt vmcnt(0)" ::: "memory"); }
;     __syncthreads();
; }
; __global__ void __launch_bounds__(512, 2) fwd_kernel(Args args_unused) {
;     ...
;                 const int grp = wg - 64 < nA ? 0 : (wg - 64 < 2 * nA ? 1 : 2);
;                 if (grp == 0) { stage_wait(c0p, (unsigned)NW, ctl + CW_BAR);
;                     for (int t = wg - 64; t < 32; t += nA) sk_mix_task(lds, t, YB, Wbr, PROJ, MIX);
;                     stage_signal(c1p); }
.LBB0_1271:
	s_or_b64 exec, exec, s[8:9]
	v_readlane_b32 s8, v253, 38
	v_readlane_b32 s9, v253, 39
	s_and_b64 vcc, exec, s[8:9]
	s_cbranch_vccz .LBB0_1292
	s_load_dwordx2 s[100:101], s[0:1], 0xf8
	s_mul_i32 s14, s96, 0x9490000
	s_mul_hi_u32 s15, s96, 0x9490000
	s_waitcnt lgkmcnt(0)
	s_add_u32 s100, s100, s14
	s_addc_u32 s101, s101, s15
	s_add_u32 s100, s100, 0xa41a000
	s_addc_u32 s101, s101, 0
	s_sub_i32 s14, s2, 64
	s_lshl_b32 s14, s14, 17
	s_add_u32 s100, s100, s14
	s_addc_u32 s101, s101, 0
	v_lshlrev_b32_e32 v212, 4, v0
	v_mov_b32_e32 v213, 0
	v_lshl_add_u64 v[212:213], s[100:101], 0, v[212:213]
	s_mov_b32 s14, 0
	s_mov_b32 s17, 0
.Lpf_a:
	global_load_dwordx4 v[216:219], v[212:213], off
	s_and_b32 s15, s14, 15
	s_cmp_eq_u32 s15, 15
	s_mov_b32 s16, 0x2000
	s_cselect_b32 s16, 0x3e2000, s16
	s_add_i32 s14, s14, 1
	v_lshl_add_u64 v[212:213], v[212:213], 0, s[16:17]
	s_cmp_lt_u32 s14, 48
	s_cbranch_scc1 .Lpf_a
	s_mov_b64 s[8:9], exec
	v_readlane_b32 s12, v253, 5
	v_readlane_b32 s13, v253, 6
	s_and_b64 s[12:13], s[8:9], s[12:13]
	s_mov_b64 exec, s[12:13]
	s_cbranch_execz .LBB0_1287
	global_load_dword v3, v2, s[10:11] sc1
	v_readlane_b32 s12, v253, 51
	s_waitcnt vmcnt(0)
	s_nop 0
	v_cmp_le_u32_e32 vcc, s12, v3
	s_cbranch_vccnz .LBB0_1286
	s_mov_b32 s18, 1
	s_branch .LBB0_1276

; __device__ __forceinline__ unsigned xb_ld(unsigned* p)              { return __hip_atomic_load(p, __ATOMIC_RELAXED, __HIP_MEMORY_SCOPE_AGENT); }
; #define XB_SPIN(cond, bar) do { unsigned _sp = 0; while (cond) { __builtin_amdgcn_s_sleep(1); \
;     if ((++_sp & 255u) == 0u) { if (xb_ld(&(bar)[XB_TMO])) break; if (_sp > XB_SPIN_CAP) { atomicAdd(&(bar)[XB_TMO], 1u); break; } } } } while (0)
; __device__ __forceinline__ void stage_wait(unsigned* ctr, unsigned want, unsigned* bar) {
;     if (threadIdx.x == 0) { XB_SPIN(xb_ld(ctr) < want, bar); __builtin_amdgcn_fence(__ATOMIC_ACQUIRE, "agent"); asm volatile("s_waitcnt vmcnt(0)" ::: "memory"); }
;     __syncthreads();
; }
; __global__ void __launch_bounds__(512, 2) fwd_kernel(Args args_unused) {
;     ...
;                 if (grp == 1) { stage_wait(c1p, (unsigned)nA, ctl + CW_BAR);
;                     for (int t = wg - 64 - nA; t < 32; t += nA) sk_resid_task(lds, t, MIX, D, Wout, XB, SSQ); }
.LBB0_1428:
	s_andn2_b64 vcc, exec, s[8:9]
	s_cbranch_vccnz .LBB0_1446
	v_readlane_b32 s8, v253, 40
	s_cmp_eq_u32 s8, 1
	s_cbranch_scc0 .LBB0_1446
	s_load_dwordx2 s[100:101], s[0:1], 0xf8
	s_mul_i32 s14, s96, 0x9490000
	s_mul_hi_u32 s15, s96, 0x9490000
	s_waitcnt lgkmcnt(0)
	s_add_u32 s100, s100, s14
	s_addc_u32 s101, s101, s15
	s_add_u32 s100, s100, 0xb01a000
	s_addc_u32 s101, s101, 0
	s_sub_i32 s14, s2, 96
	s_lshl_b32 s14, s14, 18
	s_add_u32 s100, s100, s14
	s_addc_u32 s101, s101, 0
	v_lshlrev_b32_e32 v212, 4, v0
	v_mov_b32_e32 v213, 0
	v_lshl_add_u64 v[212:213], s[100:101], 0, v[212:213]
	s_mov_b32 s14, 0
	s_mov_b32 s17, 0
.Lpf_b:
	global_load_dwordx4 v[216:219], v[212:213], off
	s_mov_b32 s16, 0x2000
	s_add_i32 s14, s14, 1
	v_lshl_add_u64 v[212:213], v[212:213], 0, s[16:17]
	s_cmp_lt_u32 s14, 32
	s_cbranch_scc1 .Lpf_b
	s_mov_b64 s[8:9], exec
	v_readlane_b32 s12, v253, 5
	v_readlane_b32 s13, v253, 6
	s_and_b64 s[12:13], s[8:9], s[12:13]
	s_mov_b64 exec, s[12:13]
	s_cbranch_execz .LBB0_1445
	global_load_dword v3, v2, s[10:11] offset:256 sc1
	v_readlane_b32 s12, v255, 0
	s_waitcnt vmcnt(0)
	s_nop 0
	v_cmp_le_u32_e32 vcc, s12, v3
	s_cbranch_vccnz .LBB0_1444
	s_mov_b32 s18, 1
	s_branch .LBB0_1434
